# adds up-front / look-ahead operand loads in the phase-B and phase-D context small GEMMs (counted vmcnt) on top of previous version
# baseline (speedup 1.0000x reference)
.LBB0_770:
	s_and_b32 s16, s22, 0xffffffc0
	s_ashr_i32 s17, s16, 31
	s_bfe_u32 s25, s23, 0x30002
	s_lshl_b64 s[18:19], s[16:17], 11
	v_lshl_add_u64 v[18:19], v[86:87], 0, s[18:19]
	s_mov_b64 s[18:19], 0x2000000
	s_lshl_b32 s17, s25, 4
	s_and_b32 s24, s23, 3
	v_lshl_add_u64 v[70:71], v[18:19], 0, s[18:19]
	s_add_i32 s18, s17, s14
	s_lshl_b32 s26, s24, 5
	s_lshl_b32 s18, s18, 1
	v_add_co_u32_e32 v70, vcc, 0x2000000, v18
	v_and_b32_e32 v82, 15, v220
	v_bfe_u32 v83, v220, 4, 2
	v_addc_co_u32_e32 v71, vcc, 0, v19, vcc
	v_add_co_u32_e32 v72, vcc, 0x2008000, v18
	v_bfe_u32 v84, v82, 2, 1
	v_lshlrev_b32_e32 v84, 11, v84
	v_addc_co_u32_e32 v73, vcc, 0, v19, vcc
	v_add_co_u32_e32 v74, vcc, 0x2010000, v18
	v_lshrrev_b32_e32 v85, 3, v82
	v_lshl_or_b32 v84, v85, 8, v84
	v_addc_co_u32_e32 v75, vcc, 0, v19, vcc
	v_add_co_u32_e32 v76, vcc, 0x2018000, v18
	v_and_b32_e32 v85, 3, v82
	v_lshl_or_b32 v84, v85, 6, v84
	v_addc_co_u32_e32 v77, vcc, 0, v19, vcc
	v_lshl_or_b32 v78, v83, 4, v84
	v_xor_b32_e32 v79, 32, v78
	v_add_u32_e32 v79, 0x200, v79
	v_add_u32_e32 v80, 0x4000, v78
	v_add_u32_e32 v81, 0x4000, v79
	v_readfirstlane_b32 s17, v220
	s_bfe_u32 s18, s23, 0x30002
	s_lshl_b32 s100, s18, 19
	s_and_b32 s18, s23, 3
	s_lshl_b32 s18, s18, 12
	s_add_i32 s100, s100, s18
	s_lshr_b32 s17, s17, 6
	s_lshl_b32 s17, s17, 16
	s_add_i32 s100, s100, s17
	s_add_u32 s20, s2, s100
	s_addc_u32 s21, s3, 0
	global_load_dwordx4 v[112:115], v[70:71], off offset:0
	global_load_dwordx4 v[116:119], v[72:73], off offset:0
	global_load_dwordx4 v[120:123], v[74:75], off offset:0
	global_load_dwordx4 v[124:127], v[76:77], off offset:0
	global_load_dwordx4 v[128:131], v78, s[20:21]
	global_load_dwordx4 v[132:135], v79, s[20:21]
	global_load_dwordx4 v[136:139], v80, s[20:21]
	global_load_dwordx4 v[140:143], v81, s[20:21]
	s_add_u32 s20, s20, 0x400
	s_addc_u32 s21, s21, 0
	global_load_dwordx4 v[144:147], v[70:71], off offset:64
	global_load_dwordx4 v[148:151], v[72:73], off offset:64
	global_load_dwordx4 v[152:155], v[74:75], off offset:64
	global_load_dwordx4 v[156:159], v[76:77], off offset:64
	global_load_dwordx4 v[160:163], v78, s[20:21]
	global_load_dwordx4 v[164:167], v79, s[20:21]
	global_load_dwordx4 v[168:171], v80, s[20:21]
	global_load_dwordx4 v[172:175], v81, s[20:21]
	s_add_u32 s20, s20, 0x7c00
	s_addc_u32 s21, s21, 0
	global_load_dwordx4 v[176:179], v[70:71], off offset:128
	global_load_dwordx4 v[180:183], v[72:73], off offset:128
	global_load_dwordx4 v[184:187], v[74:75], off offset:128
	global_load_dwordx4 v[188:191], v[76:77], off offset:128
	global_load_dwordx4 v[192:195], v78, s[20:21]
	global_load_dwordx4 v[196:199], v79, s[20:21]
	global_load_dwordx4 v[200:203], v80, s[20:21]
	global_load_dwordx4 v[204:207], v81, s[20:21]
	s_add_u32 s20, s20, 0x400
	s_addc_u32 s21, s21, 0
	s_waitcnt vmcnt(16)
	v_mfma_f32_16x16x32_bf16 v[66:69], v[128:131], v[112:115], 0
	v_mfma_f32_16x16x32_bf16 v[62:65], v[132:135], v[112:115], 0
	v_mfma_f32_16x16x32_bf16 v[58:61], v[136:139], v[112:115], 0
	v_mfma_f32_16x16x32_bf16 v[54:57], v[140:143], v[112:115], 0
	v_mfma_f32_16x16x32_bf16 v[38:41], v[128:131], v[116:119], 0
	v_mfma_f32_16x16x32_bf16 v[42:45], v[132:135], v[116:119], 0
	v_mfma_f32_16x16x32_bf16 v[46:49], v[136:139], v[116:119], 0
	v_mfma_f32_16x16x32_bf16 v[50:53], v[140:143], v[116:119], 0
	v_mfma_f32_16x16x32_bf16 v[30:33], v[128:131], v[120:123], 0
	v_mfma_f32_16x16x32_bf16 v[34:37], v[132:135], v[120:123], 0
	v_mfma_f32_16x16x32_bf16 v[6:9], v[136:139], v[120:123], 0
	v_mfma_f32_16x16x32_bf16 v[10:13], v[140:143], v[120:123], 0
	v_mfma_f32_16x16x32_bf16 v[14:17], v[128:131], v[124:127], 0
	v_mfma_f32_16x16x32_bf16 v[18:21], v[132:135], v[124:127], 0
	v_mfma_f32_16x16x32_bf16 v[22:25], v[136:139], v[124:127], 0
	v_mfma_f32_16x16x32_bf16 v[26:29], v[140:143], v[124:127], 0
	global_load_dwordx4 v[112:115], v[70:71], off offset:192
	global_load_dwordx4 v[116:119], v[72:73], off offset:192
	global_load_dwordx4 v[120:123], v[74:75], off offset:192
	global_load_dwordx4 v[124:127], v[76:77], off offset:192
	global_load_dwordx4 v[128:131], v78, s[20:21]
	global_load_dwordx4 v[132:135], v79, s[20:21]
	global_load_dwordx4 v[136:139], v80, s[20:21]
	global_load_dwordx4 v[140:143], v81, s[20:21]
	s_waitcnt vmcnt(16)
	v_mfma_f32_16x16x32_bf16 v[66:69], v[160:163], v[144:147], v[66:69]
	v_mfma_f32_16x16x32_bf16 v[62:65], v[164:167], v[144:147], v[62:65]
	v_mfma_f32_16x16x32_bf16 v[58:61], v[168:171], v[144:147], v[58:61]
	v_mfma_f32_16x16x32_bf16 v[54:57], v[172:175], v[144:147], v[54:57]
	v_mfma_f32_16x16x32_bf16 v[38:41], v[160:163], v[148:151], v[38:41]
	v_mfma_f32_16x16x32_bf16 v[42:45], v[164:167], v[148:151], v[42:45]
	v_mfma_f32_16x16x32_bf16 v[46:49], v[168:171], v[148:151], v[46:49]
	v_mfma_f32_16x16x32_bf16 v[50:53], v[172:175], v[148:151], v[50:53]
	v_mfma_f32_16x16x32_bf16 v[30:33], v[160:163], v[152:155], v[30:33]
	v_mfma_f32_16x16x32_bf16 v[34:37], v[164:167], v[152:155], v[34:37]
	v_mfma_f32_16x16x32_bf16 v[6:9], v[168:171], v[152:155], v[6:9]
	v_mfma_f32_16x16x32_bf16 v[10:13], v[172:175], v[152:155], v[10:13]
	v_mfma_f32_16x16x32_bf16 v[14:17], v[160:163], v[156:159], v[14:17]
	v_mfma_f32_16x16x32_bf16 v[18:21], v[164:167], v[156:159], v[18:21]
	v_mfma_f32_16x16x32_bf16 v[22:25], v[168:171], v[156:159], v[22:25]
	v_mfma_f32_16x16x32_bf16 v[26:29], v[172:175], v[156:159], v[26:29]
	s_waitcnt vmcnt(8)
	v_mfma_f32_16x16x32_bf16 v[66:69], v[192:195], v[176:179], v[66:69]
	v_mfma_f32_16x16x32_bf16 v[62:65], v[196:199], v[176:179], v[62:65]
	v_mfma_f32_16x16x32_bf16 v[58:61], v[200:203], v[176:179], v[58:61]
	v_mfma_f32_16x16x32_bf16 v[54:57], v[204:207], v[176:179], v[54:57]
	v_mfma_f32_16x16x32_bf16 v[38:41], v[192:195], v[180:183], v[38:41]
	v_mfma_f32_16x16x32_bf16 v[42:45], v[196:199], v[180:183], v[42:45]
	v_mfma_f32_16x16x32_bf16 v[46:49], v[200:203], v[180:183], v[46:49]
	v_mfma_f32_16x16x32_bf16 v[50:53], v[204:207], v[180:183], v[50:53]
	v_mfma_f32_16x16x32_bf16 v[30:33], v[192:195], v[184:187], v[30:33]
	v_mfma_f32_16x16x32_bf16 v[34:37], v[196:199], v[184:187], v[34:37]
	v_mfma_f32_16x16x32_bf16 v[6:9], v[200:203], v[184:187], v[6:9]
	v_mfma_f32_16x16x32_bf16 v[10:13], v[204:207], v[184:187], v[10:13]
	v_mfma_f32_16x16x32_bf16 v[14:17], v[192:195], v[188:191], v[14:17]
	v_mfma_f32_16x16x32_bf16 v[18:21], v[196:199], v[188:191], v[18:21]
	v_mfma_f32_16x16x32_bf16 v[22:25], v[200:203], v[188:191], v[22:25]
	v_mfma_f32_16x16x32_bf16 v[26:29], v[204:207], v[188:191], v[26:29]
	s_waitcnt vmcnt(0)
	v_mfma_f32_16x16x32_bf16 v[66:69], v[128:131], v[112:115], v[66:69]
	v_mfma_f32_16x16x32_bf16 v[62:65], v[132:135], v[112:115], v[62:65]
	v_mfma_f32_16x16x32_bf16 v[58:61], v[136:139], v[112:115], v[58:61]
	v_mfma_f32_16x16x32_bf16 v[54:57], v[140:143], v[112:115], v[54:57]
	v_mfma_f32_16x16x32_bf16 v[38:41], v[128:131], v[116:119], v[38:41]
	v_mfma_f32_16x16x32_bf16 v[42:45], v[132:135], v[116:119], v[42:45]
	v_mfma_f32_16x16x32_bf16 v[46:49], v[136:139], v[116:119], v[46:49]
	v_mfma_f32_16x16x32_bf16 v[50:53], v[140:143], v[116:119], v[50:53]
	v_mfma_f32_16x16x32_bf16 v[30:33], v[128:131], v[120:123], v[30:33]
	v_mfma_f32_16x16x32_bf16 v[34:37], v[132:135], v[120:123], v[34:37]
	v_mfma_f32_16x16x32_bf16 v[6:9], v[136:139], v[120:123], v[6:9]
	v_mfma_f32_16x16x32_bf16 v[10:13], v[140:143], v[120:123], v[10:13]
	v_mfma_f32_16x16x32_bf16 v[14:17], v[128:131], v[124:127], v[14:17]
	v_mfma_f32_16x16x32_bf16 v[18:21], v[132:135], v[124:127], v[18:21]
	v_mfma_f32_16x16x32_bf16 v[22:25], v[136:139], v[124:127], v[22:25]
	v_mfma_f32_16x16x32_bf16 v[26:29], v[140:143], v[124:127], v[26:29]
	s_cmp_lt_i32 s25, 1
	ds_write_b128 v110, v[66:69]
	ds_write_b128 v110, v[62:65] offset:64
	ds_write_b128 v110, v[58:61] offset:128
	ds_write_b128 v110, v[54:57] offset:192
	ds_write_b128 v110, v[38:41] offset:4096
	ds_write_b128 v110, v[42:45] offset:4160
	ds_write_b128 v110, v[46:49] offset:4224
	ds_write_b128 v110, v[50:53] offset:4288
	ds_write_b128 v110, v[30:33] offset:8192
	ds_write_b128 v110, v[34:37] offset:8256
	ds_write_b128 v110, v[6:9] offset:8320
	ds_write_b128 v110, v[10:13] offset:8384
	ds_write_b128 v110, v[14:17] offset:12288
	ds_write_b128 v110, v[18:21] offset:12352
	ds_write_b128 v110, v[22:25] offset:12416
	ds_write_b128 v110, v[26:29] offset:12480
	s_waitcnt lgkmcnt(0)
	s_barrier
	ds_read_b128 v[6:9], v101
	ds_read_b128 v[10:13], v101 offset:16
	ds_read_b128 v[14:17], v101 offset:16384
	ds_read_b128 v[22:25], v101 offset:16400
	ds_read_b128 v[26:29], v101 offset:32768
	ds_read_b128 v[30:33], v101 offset:32784
	ds_read_b128 v[34:37], v101 offset:49152
	ds_read_b128 v[38:41], v101 offset:49168
	ds_read_b128 v[42:45], v102
	ds_read_b128 v[46:49], v103
	ds_read_b128 v[50:53], v104
	ds_read_b128 v[54:57], v105
	ds_read_b128 v[58:61], v106
	ds_read_b128 v[62:65], v107
	s_waitcnt lgkmcnt(13)
	v_pk_add_f32 v[6:7], v[6:7], 0 op_sel_hi:[1,0]
	v_add_u32_e32 v20, s16, v100
	s_waitcnt lgkmcnt(11)
	v_pk_add_f32 v[6:7], v[14:15], v[6:7]
	s_mov_b64 s[16:17], -1
	s_waitcnt lgkmcnt(9)
	v_pk_add_f32 v[6:7], v[26:27], v[6:7]
	s_waitcnt lgkmcnt(7)
	v_pk_add_f32 v[6:7], v[34:35], v[6:7]
	s_waitcnt lgkmcnt(5)
	v_pk_add_f32 v[6:7], v[42:43], v[6:7]
	s_waitcnt lgkmcnt(3)
	v_pk_add_f32 v[6:7], v[50:51], v[6:7]
	s_waitcnt lgkmcnt(1)
	v_pk_add_f32 v[14:15], v[58:59], v[6:7]
	v_pk_add_f32 v[6:7], v[8:9], 0 op_sel_hi:[1,0]
	s_nop 0
	v_pk_add_f32 v[6:7], v[16:17], v[6:7]
	s_nop 0
	v_pk_add_f32 v[6:7], v[28:29], v[6:7]
	s_nop 0
	v_pk_add_f32 v[6:7], v[36:37], v[6:7]
	s_nop 0
	v_pk_add_f32 v[6:7], v[44:45], v[6:7]
	s_nop 0
	v_pk_add_f32 v[6:7], v[52:53], v[6:7]
	s_nop 0
	v_pk_add_f32 v[16:17], v[60:61], v[6:7]
	v_pk_add_f32 v[6:7], v[10:11], 0 op_sel_hi:[1,0]
	s_nop 0
	v_pk_add_f32 v[6:7], v[22:23], v[6:7]
	s_nop 0
	v_pk_add_f32 v[6:7], v[30:31], v[6:7]
	s_nop 0
	v_pk_add_f32 v[6:7], v[38:39], v[6:7]
	s_nop 0
	v_pk_add_f32 v[6:7], v[46:47], v[6:7]
	s_nop 0
	v_pk_add_f32 v[6:7], v[54:55], v[6:7]
	s_waitcnt lgkmcnt(0)
	v_pk_add_f32 v[22:23], v[62:63], v[6:7]
	v_pk_add_f32 v[6:7], v[12:13], 0 op_sel_hi:[1,0]
	s_nop 0
	v_pk_add_f32 v[6:7], v[24:25], v[6:7]
	s_nop 0
	v_pk_add_f32 v[6:7], v[32:33], v[6:7]
	s_nop 0
	v_pk_add_f32 v[10:11], v[40:41], v[6:7]
	ds_read_b128 v[6:9], v108
	v_pk_add_f32 v[18:19], v[48:49], v[10:11]
	ds_read_b128 v[10:13], v109
	v_pk_add_f32 v[18:19], v[56:57], v[18:19]
	s_waitcnt lgkmcnt(1)
	v_pk_add_f32 v[16:17], v[8:9], v[16:17]
	v_pk_add_f32 v[24:25], v[64:65], v[18:19]
	v_pk_add_f32 v[18:19], v[6:7], v[14:15]
	s_waitcnt lgkmcnt(0)
	v_pk_add_f32 v[14:15], v[10:11], v[22:23]
	v_pk_add_f32 v[12:13], v[12:13], v[24:25]
	v_add_u32_e32 v10, 0x4000, v20
	s_cbranch_scc1 .LBB0_794
	s_cmp_lg_u32 s25, 1
	s_cbranch_scc0 .LBB0_791
	s_and_b32 s16, s23, 24
	s_cmp_eq_u32 s16, 8
	s_cselect_b64 s[16:17], -1, 0
	v_ashrrev_i32_e32 v21, 8, v20
	s_and_b64 vcc, exec, s[16:17]
	s_cbranch_vccnz .LBB0_785
	s_cmp_lg_u32 s25, 4
	s_cselect_b64 s[18:19], -1, 0
	s_cmp_eq_u32 s25, 4
	s_cselect_b64 s[16:17], -1, 0
	s_cmp_lt_u32 s24, 2
	s_cselect_b64 s[20:21], -1, 0
	s_and_b64 s[16:17], s[16:17], s[20:21]
	s_andn2_b64 vcc, exec, s[16:17]
	s_mov_b64 s[16:17], -1
	s_cbranch_vccz .LBB0_785
	s_and_b64 vcc, exec, s[18:19]
	s_cbranch_vccz .LBB0_782
	s_cmp_eq_u32 s25, 5
	s_cbranch_scc1 .LBB0_779
	v_and_b32_e32 v6, 64, v224
	v_xor_b32_e32 v0, 4, v224
	v_add_u32_e32 v6, 64, v6
	v_cmp_lt_i32_e32 vcc, v0, v6
	s_nop 1
	v_cndmask_b32_e32 v0, v224, v0, vcc
	v_lshlrev_b32_e32 v23, 2, v0
	ds_bpermute_b32 v0, v23, v18
	ds_bpermute_b32 v6, v23, v19
	ds_bpermute_b32 v7, v23, v16
	ds_bpermute_b32 v8, v23, v17
	ds_bpermute_b32 v9, v23, v14
	ds_bpermute_b32 v11, v23, v15
	ds_bpermute_b32 v22, v23, v12
	ds_bpermute_b32 v23, v23, v13
	s_and_saveexec_b64 s[16:17], s[0:1]
	s_cbranch_execz .LBB0_778
	s_waitcnt lgkmcnt(2)
	v_mul_f32_e32 v26, v15, v11
	v_ashrrev_i32_e32 v11, 31, v10
	v_mul_f32_e32 v27, v16, v7
	v_mul_f32_e32 v28, v19, v6
	v_lshlrev_b64 v[6:7], 9, v[10:11]
	v_lshl_add_u64 v[6:7], s[4:5], 0, v[6:7]
	s_lshl_b32 s80, s25, 8
	v_lshl_add_u64 v[6:7], v[6:7], 0, s[80:81]
	s_lshl_b32 s80, s26, 1
	v_mul_f32_e32 v29, v18, v0
	v_lshl_add_u64 v[6:7], v[6:7], 0, s[80:81]
	v_lshlrev_b32_e32 v0, 1, v88
	s_waitcnt lgkmcnt(0)
	v_mul_f32_e32 v24, v13, v23
	v_mul_f32_e32 v25, v12, v22
	v_lshl_add_u64 v[22:23], v[6:7], 0, v[0:1]
	v_add_co_u32_e32 v22, vcc, 0xa97f000, v22
	v_mul_f32_e32 v9, v14, v9
	v_mul_f32_e32 v8, v17, v8
	v_addc_co_u32_e32 v23, vcc, 0, v23, vcc
	v_cvt_pk_bf16_f32 v6, v29, v28
	v_cvt_pk_bf16_f32 v7, v27, v8
	v_cvt_pk_bf16_f32 v8, v9, v26
	v_cvt_pk_bf16_f32 v9, v25, v24
	global_store_dwordx4 v[22:23], v[6:9], off offset:2560

.LBB0_1092:
	s_and_b32 s8, s13, 0xffffffe0
	s_ashr_i32 s9, s8, 31
	s_lshl_b64 s[10:11], s[8:9], 11
	v_lshl_add_u64 v[6:7], v[36:37], 0, s[10:11]
	s_lshl_b32 s10, s14, 2
	s_and_b32 s15, s10, 48
	s_lshl_b32 s10, s15, 1
	s_bfe_u32 s16, s14, 0x10001
	s_add_i32 s10, s10, s7
	s_lshl_b32 s17, s14, 6
	s_or_b32 s10, s10, s16
	s_ashr_i32 s11, s10, 31
	v_and_or_b32 v0, s17, 64, v44
	s_and_b32 s9, s17, 0x3c0
	s_lshl_b64 s[10:11], s[10:11], 14
	v_lshlrev_b32_e32 v55, 7, v0
	s_add_u32 s10, s3, s10
	v_or_b32_e32 v14, v55, v45
	v_or_b32_e32 v22, v55, v48
	s_addc_u32 s11, s6, s11
	v_or_b32_e32 v0, v14, v46
	v_bitop3_b32 v84, v14, 32, v47 bitop3:0x36
	v_or_b32_e32 v85, v22, v46
	v_bitop3_b32 v88, v22, 32, v47 bitop3:0x36
	v_add_co_u32_e32 v56, vcc, 0x2000000, v6
	v_and_b32_e32 v116, 15, v220
	v_bfe_u32 v117, v220, 4, 2
	v_addc_co_u32_e32 v57, vcc, 0, v7, vcc
	v_add_co_u32_e32 v58, vcc, 0x2008000, v6
	v_bfe_u32 v118, v116, 2, 1
	v_lshlrev_b32_e32 v118, 11, v118
	v_addc_co_u32_e32 v59, vcc, 0, v7, vcc
	v_lshrrev_b32_e32 v120, 3, v116
	v_lshl_or_b32 v118, v120, 8, v118
	v_and_b32_e32 v120, 3, v116
	v_lshl_or_b32 v118, v120, 6, v118
	v_lshl_or_b32 v84, v117, 4, v118
	v_xor_b32_e32 v85, 32, v84
	v_add_u32_e32 v85, 0x200, v85
	v_add_u32_e32 v86, 0x1000, v84
	v_add_u32_e32 v87, 0x1000, v85
	v_readfirstlane_b32 s15, v220
	s_and_b32 s17, s14, 15
	s_lshr_b32 s100, s17, 2
	s_lshl_b32 s100, s100, 19
	s_bfe_u32 s16, s17, 0x10001
	s_lshl_b32 s16, s16, 14
	s_add_i32 s100, s100, s16
	s_and_b32 s16, s17, 1
	s_lshl_b32 s16, s16, 13
	s_add_i32 s100, s100, s16
	s_lshr_b32 s15, s15, 6
	s_lshl_b32 s15, s15, 16
	s_add_i32 s100, s100, s15
	s_add_u32 s10, s3, s100
	s_addc_u32 s11, s6, 0
	global_load_dwordx4 v[72:75], v[56:57], off offset:0
	global_load_dwordx4 v[76:79], v[58:59], off offset:0
	global_load_dwordx4 v[80:83], v84, s[10:11]
	global_load_dwordx4 v[88:91], v85, s[10:11]
	global_load_dwordx4 v[92:95], v86, s[10:11]
	global_load_dwordx4 v[96:99], v87, s[10:11]
	s_add_u32 s10, s10, 0x400
	s_addc_u32 s11, s11, 0
	global_load_dwordx4 v[100:103], v[56:57], off offset:64
	global_load_dwordx4 v[104:107], v[58:59], off offset:64
	global_load_dwordx4 v[108:111], v84, s[10:11]
	global_load_dwordx4 v[112:115], v85, s[10:11]
	global_load_dwordx4 v[124:127], v86, s[10:11]
	global_load_dwordx4 v[128:131], v87, s[10:11]
	s_add_u32 s10, s10, 0x7c00
	s_addc_u32 s11, s11, 0
	global_load_dwordx4 v[132:135], v[56:57], off offset:128
	global_load_dwordx4 v[136:139], v[58:59], off offset:128
	global_load_dwordx4 v[140:143], v84, s[10:11]
	global_load_dwordx4 v[144:147], v85, s[10:11]
	global_load_dwordx4 v[148:151], v86, s[10:11]
	global_load_dwordx4 v[152:155], v87, s[10:11]
	s_add_u32 s10, s10, 0x400
	s_addc_u32 s11, s11, 0
	global_load_dwordx4 v[156:159], v[56:57], off offset:192
	global_load_dwordx4 v[160:163], v[58:59], off offset:192
	global_load_dwordx4 v[164:167], v84, s[10:11]
	global_load_dwordx4 v[168:171], v85, s[10:11]
	global_load_dwordx4 v[172:175], v86, s[10:11]
	global_load_dwordx4 v[176:179], v87, s[10:11]
	s_waitcnt vmcnt(18)
	v_mfma_f32_16x16x32_bf16 v[30:33], v[80:83], v[72:75], 0
	v_mfma_f32_16x16x32_bf16 v[26:29], v[88:91], v[72:75], 0
	v_mfma_f32_16x16x32_bf16 v[22:25], v[92:95], v[72:75], 0
	v_mfma_f32_16x16x32_bf16 v[18:21], v[96:99], v[72:75], 0
	v_mfma_f32_16x16x32_bf16 v[2:5], v[80:83], v[76:79], 0
	v_mfma_f32_16x16x32_bf16 v[6:9], v[88:91], v[76:79], 0
	v_mfma_f32_16x16x32_bf16 v[10:13], v[92:95], v[76:79], 0
	v_mfma_f32_16x16x32_bf16 v[14:17], v[96:99], v[76:79], 0
	s_waitcnt vmcnt(12)
	v_mfma_f32_16x16x32_bf16 v[30:33], v[108:111], v[100:103], v[30:33]
	v_mfma_f32_16x16x32_bf16 v[26:29], v[112:115], v[100:103], v[26:29]
	v_mfma_f32_16x16x32_bf16 v[22:25], v[124:127], v[100:103], v[22:25]
	v_mfma_f32_16x16x32_bf16 v[18:21], v[128:131], v[100:103], v[18:21]
	v_mfma_f32_16x16x32_bf16 v[2:5], v[108:111], v[104:107], v[2:5]
	v_mfma_f32_16x16x32_bf16 v[6:9], v[112:115], v[104:107], v[6:9]
	v_mfma_f32_16x16x32_bf16 v[10:13], v[124:127], v[104:107], v[10:13]
	v_mfma_f32_16x16x32_bf16 v[14:17], v[128:131], v[104:107], v[14:17]
	s_waitcnt vmcnt(6)
	v_mfma_f32_16x16x32_bf16 v[30:33], v[140:143], v[132:135], v[30:33]
	v_mfma_f32_16x16x32_bf16 v[26:29], v[144:147], v[132:135], v[26:29]
	v_mfma_f32_16x16x32_bf16 v[22:25], v[148:151], v[132:135], v[22:25]
	v_mfma_f32_16x16x32_bf16 v[18:21], v[152:155], v[132:135], v[18:21]
	v_mfma_f32_16x16x32_bf16 v[2:5], v[140:143], v[136:139], v[2:5]
	v_mfma_f32_16x16x32_bf16 v[6:9], v[144:147], v[136:139], v[6:9]
	v_mfma_f32_16x16x32_bf16 v[10:13], v[148:151], v[136:139], v[10:13]
	v_mfma_f32_16x16x32_bf16 v[14:17], v[152:155], v[136:139], v[14:17]
	s_waitcnt vmcnt(0)
	v_mfma_f32_16x16x32_bf16 v[30:33], v[164:167], v[156:159], v[30:33]
	v_mfma_f32_16x16x32_bf16 v[26:29], v[168:171], v[156:159], v[26:29]
	v_mfma_f32_16x16x32_bf16 v[22:25], v[172:175], v[156:159], v[22:25]
	v_mfma_f32_16x16x32_bf16 v[18:21], v[176:179], v[156:159], v[18:21]
	v_mfma_f32_16x16x32_bf16 v[2:5], v[164:167], v[160:163], v[2:5]
	v_mfma_f32_16x16x32_bf16 v[6:9], v[168:171], v[160:163], v[6:9]
	v_mfma_f32_16x16x32_bf16 v[10:13], v[172:175], v[160:163], v[10:13]
	v_mfma_f32_16x16x32_bf16 v[14:17], v[176:179], v[160:163], v[14:17]
	v_or_b32_e32 v0, s9, v52
	v_lshlrev_b32_e32 v0, 2, v0
	s_add_i32 s14, s14, s42
	s_add_i32 s13, s13, s68
	s_cmp_ge_i32 s14, s44
	ds_write_b128 v54, v[30:33]
	ds_write_b128 v54, v[26:29] offset:64
	ds_write_b128 v54, v[22:25] offset:128
	s_nop 0
	ds_write_b128 v54, v[18:21] offset:192
	ds_write_b128 v54, v[2:5] offset:4096
	ds_write_b128 v54, v[6:9] offset:4160
	ds_write_b128 v54, v[10:13] offset:4224
	ds_write_b128 v54, v[14:17] offset:4288
	s_waitcnt lgkmcnt(0)
	s_barrier
	ds_read_b128 v[2:5], v53
	v_add_u32_e32 v6, s8, v51
	v_ashrrev_i32_e32 v7, 31, v6
	v_lshlrev_b64 v[14:15], 12, v[6:7]
	v_lshl_add_u64 v[6:7], v[34:35], 0, v[14:15]
	s_waitcnt lgkmcnt(0)
	v_pk_add_f32 v[8:9], v[4:5], 0 op_sel_hi:[1,0]
	v_pk_add_f32 v[10:11], v[2:3], 0 op_sel_hi:[1,0]
	ds_read_b128 v[2:5], v53 offset:8192
	v_lshl_add_u64 v[6:7], v[6:7], 0, v[0:1]
	s_waitcnt lgkmcnt(0)
	v_pk_add_f32 v[8:9], v[8:9], v[4:5]
	v_pk_add_f32 v[10:11], v[10:11], v[2:3]
	ds_read_b128 v[2:5], v53 offset:16384
	s_waitcnt lgkmcnt(0)
	v_pk_add_f32 v[8:9], v[8:9], v[4:5]
	v_pk_add_f32 v[10:11], v[10:11], v[2:3]
	ds_read_b128 v[2:5], v53 offset:24576
	s_waitcnt lgkmcnt(0)
	v_pk_add_f32 v[8:9], v[8:9], v[4:5]
	v_pk_add_f32 v[10:11], v[10:11], v[2:3]
	ds_read_b128 v[2:5], v53 offset:32768
	s_waitcnt lgkmcnt(0)
	v_pk_add_f32 v[8:9], v[8:9], v[4:5]
	v_pk_add_f32 v[10:11], v[10:11], v[2:3]
	ds_read_b128 v[2:5], v53 offset:40960
	s_waitcnt lgkmcnt(0)
	v_pk_add_f32 v[8:9], v[8:9], v[4:5]
	v_pk_add_f32 v[10:11], v[10:11], v[2:3]
	ds_read_b128 v[2:5], v53 offset:49152
	s_waitcnt lgkmcnt(0)
	v_pk_add_f32 v[8:9], v[8:9], v[4:5]
	v_pk_add_f32 v[10:11], v[10:11], v[2:3]
	ds_read_b128 v[2:5], v53 offset:57344
	s_waitcnt lgkmcnt(0)
	v_pk_add_f32 v[12:13], v[8:9], v[4:5]
	v_pk_add_f32 v[10:11], v[10:11], v[2:3]
	global_load_dwordx4 v[2:5], v0, s[4:5]
	s_nop 0
	global_load_dwordx4 v[6:9], v[6:7], off
	s_waitcnt vmcnt(0)
	v_pk_fma_f32 v[2:3], v[10:11], v[2:3], v[6:7]
	v_lshl_add_u64 v[6:7], s[0:1], 0, v[14:15]
	v_pk_fma_f32 v[4:5], v[12:13], v[4:5], v[8:9]
	v_lshl_add_u64 v[6:7], v[6:7], 0, v[0:1]
	global_store_dwordx4 v[6:7], v[2:5], off
	s_barrier
	s_cbranch_scc0 .LBB0_1092
